# early L1 invalidate issued by wave 1 right after the WG barrier (own vmcnt, does not delay wave 0's arrival ticket); exit barrier waits vmcnt(0)
# baseline (speedup 1.0000x reference)
; DEVI void xcd_barrier(const XcdBarrier& b) {
;     ...
;   }
;   __syncthreads();
.LBB0_11:
	s_or_b64 exec, exec, s[4:5]
	s_waitcnt vmcnt(0) lgkmcnt(0)
	s_barrier

; DEVI void xcd_barrier(const XcdBarrier& b) {
;   asm volatile("s_waitcnt vmcnt(0)" ::: "memory");
;   __syncthreads();
;   if (threadIdx.x == 0) {
.LBB0_929:
	s_waitcnt vmcnt(0)
	v_readlane_b32 s20, v242, 37
	v_readlane_b32 s21, v242, 38
	s_waitcnt vmcnt(0)
	s_barrier
	v_readfirstlane_b32 s26, v220
	s_cmp_lg_u32 s26, 64
	s_cbranch_scc1 .Lxb_w1skip
	s_sleep 4
	buffer_inv sc1
.Lxb_w1skip:
	s_and_saveexec_b64 s[4:5], s[20:21]
	s_cbranch_execnz .LBB0_930
	s_getpc_b64 s[98:99]
